# attention loops: drop NaN-canonicalizing v_max pairs and the 0+x row-sum seed (8 VALU per 64-key iteration in both loops), on top of v7
# speedup vs baseline: 1.0307x; 1.0132x over previous
.LBB0_436:
	v_add3_u32 v198, s20, v180, v182
	ds_read_b128 v[82:85], v198
	ds_read_b128 v[186:189], v198 offset:32
	s_mulk_i32 s24, 0x4800
	v_add_u32_e32 v221, s24, v185
	v_sub_f32_e32 v202, v2, v184
	s_waitcnt lgkmcnt(1)
	v_mfma_f32_32x32x16_bf16 v[82:97], v[82:85], v[98:101], 0
	v_sub_f32_e32 v203, v3, v184
	v_sub_f32_e32 v204, v4, v184
	v_sub_f32_e32 v205, v5, v184
	v_sub_f32_e32 v206, v6, v184
	v_sub_f32_e32 v207, v7, v184
	v_sub_f32_e32 v208, v8, v184
	v_sub_f32_e32 v209, v9, v184
	s_waitcnt lgkmcnt(0)
	v_mfma_f32_32x32x16_bf16 v[82:97], v[186:189], v[102:105], v[82:97]
	ds_read_b128 v[186:189], v198 offset:64
	ds_read_b128 v[190:193], v198 offset:96
	v_exp_f32_e32 v217, v202
	v_exp_f32_e32 v218, v203
	v_exp_f32_e32 v219, v204
	v_exp_f32_e32 v220, v205
	v_exp_f32_e32 v206, v206
	v_exp_f32_e32 v207, v207
	s_waitcnt lgkmcnt(1)
	v_mfma_f32_32x32x16_bf16 v[82:97], v[186:189], v[106:109], v[82:97]
	v_exp_f32_e32 v208, v208
	v_exp_f32_e32 v209, v209
	v_sub_f32_e32 v210, v10, v184
	v_sub_f32_e32 v211, v11, v184
	v_sub_f32_e32 v212, v12, v184
	v_sub_f32_e32 v213, v13, v184
	v_sub_f32_e32 v214, v14, v184
	s_waitcnt lgkmcnt(0)
	v_mfma_f32_32x32x16_bf16 v[82:97], v[190:193], v[110:113], v[82:97]
	ds_read_b128 v[186:189], v198 offset:128
	ds_read_b128 v[190:193], v198 offset:160
	v_sub_f32_e32 v215, v15, v184
	v_sub_f32_e32 v216, v16, v184
	v_exp_f32_e32 v210, v210
	v_exp_f32_e32 v211, v211
	v_exp_f32_e32 v212, v212
	v_exp_f32_e32 v213, v213
	s_waitcnt lgkmcnt(1)
	v_mfma_f32_32x32x16_bf16 v[82:97], v[186:189], v[114:117], v[82:97]
	ds_read_b128 v[186:189], v198 offset:192
	v_exp_f32_e32 v214, v214
	v_exp_f32_e32 v215, v215
	v_exp_f32_e32 v216, v216
	v_max_f32_e32 v2, v2, v3
	s_waitcnt lgkmcnt(1)
	v_mfma_f32_32x32x16_bf16 v[82:97], v[190:193], v[118:121], v[82:97]
	ds_read_b128 v[190:193], v198 offset:224
	v_max3_f32 v2, v2, v4, v5
	v_max3_f32 v2, v2, v6, v7
	v_max3_f32 v2, v2, v8, v9
	v_max3_f32 v6, v2, v10, v11
	v_max3_f32 v6, v6, v12, v13
	v_max3_f32 v6, v6, v14, v15
	s_waitcnt lgkmcnt(1)
	v_mfma_f32_32x32x16_bf16 v[82:97], v[186:189], v[122:125], v[82:97]
	ds_read_b128 v[186:189], v198 offset:256
	v_max3_f32 v10, v6, v16, v17
	v_add_f32_e32 v12, v218, v217
	ds_bpermute_b32 v11, v178, v10
	s_waitcnt lgkmcnt(2)
	v_mfma_f32_32x32x16_bf16 v[82:97], v[190:193], v[126:129], v[82:97]
	ds_read_b128 v[190:193], v198 offset:288
	ds_read_b128 v[194:197], v198 offset:320
	ds_read_b128 v[198:201], v198 offset:352
	s_waitcnt lgkmcnt(4)
	v_mfma_f32_32x32x16_bf16 v[82:97], v[186:189], v[130:133], v[82:97]
	ds_read_b128 v[186:189], v221 offset:51264
	s_waitcnt lgkmcnt(3)
	v_mfma_f32_32x32x16_bf16 v[82:97], v[190:193], v[134:137], v[82:97]
	ds_read_b128 v[190:193], v221 offset:51296
	s_waitcnt lgkmcnt(3)
	v_mfma_f32_32x32x16_bf16 v[82:97], v[194:197], v[138:141], v[82:97]
	v_cvt_pk_bf16_f32 v194, v217, v218
	v_cvt_pk_bf16_f32 v195, v219, v220
	v_cvt_pk_bf16_f32 v196, v206, v207
	v_cvt_pk_bf16_f32 v197, v208, v209
	s_waitcnt lgkmcnt(1)
	s_nop 0
	v_mfma_f32_32x32x16_bf16 v[18:33], v[186:189], v[194:197], v[18:33]
	v_sub_f32_e32 v186, v17, v184
	v_exp_f32_e32 v222, v186
	v_cvt_pk_bf16_f32 v186, v210, v211
	v_cvt_pk_bf16_f32 v187, v212, v213
	v_cvt_pk_bf16_f32 v188, v214, v215
	v_cvt_pk_bf16_f32 v189, v216, v222
	s_waitcnt lgkmcnt(0)
	s_nop 0
	v_mfma_f32_32x32x16_bf16 v[18:33], v[190:193], v[186:189], v[18:33]
	ds_read_b128 v[190:193], v221 offset:55872
	ds_read_b128 v[202:205], v221 offset:55904
	ds_read_b128 v[2:5], v221 offset:60512
	ds_read_b128 v[6:9], v221 offset:65088
	s_waitcnt lgkmcnt(3)
	v_mfma_f32_32x32x16_bf16 v[34:49], v[190:193], v[194:197], v[34:49]
	ds_read_b128 v[190:193], v221 offset:60480
	s_waitcnt lgkmcnt(0)
	v_mfma_f32_32x32x16_bf16 v[50:65], v[190:193], v[194:197], v[50:65]
	v_mfma_f32_32x32x16_bf16 v[50:65], v[2:5], v[186:189], v[50:65]
	v_add_f32_e32 v2, v219, v12
	v_add_f32_e32 v2, v220, v2
	v_add_f32_e32 v2, v206, v2
	v_add_f32_e32 v2, v207, v2
	v_add_f32_e32 v2, v208, v2
	v_add_f32_e32 v12, v209, v2
	ds_read_b128 v[2:5], v221 offset:65120
	v_mfma_f32_32x32x16_bf16 v[66:81], v[6:9], v[194:197], v[66:81]
	v_add_f32_e32 v6, v210, v12
	v_add_f32_e32 v6, v211, v6
	v_add_f32_e32 v6, v212, v6
	v_add_f32_e32 v6, v213, v6
	v_add_f32_e32 v6, v214, v6
	v_add_f32_e32 v6, v215, v6
	v_add_f32_e32 v6, v216, v6
	s_waitcnt lgkmcnt(0)
	v_mfma_f32_32x32x16_bf16 v[66:81], v[2:5], v[186:189], v[66:81]
	v_add_f32_e32 v2, v222, v6
	v_add_f32_e32 v183, v183, v2
	v_mfma_f32_32x32x16_bf16 v[34:49], v[202:205], v[186:189], v[34:49]
	v_max_f32_e32 v186, v10, v11
	v_sub_f32_e32 v202, v186, v184
	v_cmp_lt_f32_e32 vcc, s2, v202
	v_mfma_f32_32x32x16_bf16 v[2:17], v[198:201], v[142:145], v[82:97]
	s_cbranch_vccz .LBB0_438
	v_max_f32_e32 v202, v202, v202
	v_max_f32_e32 v203, 0, v202
	v_exp_f32_e64 v202, -v203
	v_add_f32_e32 v184, v184, v203
	v_mul_f32_e32 v183, v183, v202
	v_pk_mul_f32 v[32:33], v[202:203], v[32:33] op_sel_hi:[0,1]
	v_pk_mul_f32 v[30:31], v[202:203], v[30:31] op_sel_hi:[0,1]
	v_pk_mul_f32 v[28:29], v[202:203], v[28:29] op_sel_hi:[0,1]
	v_pk_mul_f32 v[26:27], v[202:203], v[26:27] op_sel_hi:[0,1]
	v_pk_mul_f32 v[24:25], v[202:203], v[24:25] op_sel_hi:[0,1]
	v_pk_mul_f32 v[22:23], v[202:203], v[22:23] op_sel_hi:[0,1]
	v_pk_mul_f32 v[20:21], v[202:203], v[20:21] op_sel_hi:[0,1]
	v_pk_mul_f32 v[18:19], v[202:203], v[18:19] op_sel_hi:[0,1]
	v_pk_mul_f32 v[48:49], v[202:203], v[48:49] op_sel_hi:[0,1]
	v_pk_mul_f32 v[46:47], v[202:203], v[46:47] op_sel_hi:[0,1]
	v_pk_mul_f32 v[44:45], v[202:203], v[44:45] op_sel_hi:[0,1]
	v_pk_mul_f32 v[42:43], v[202:203], v[42:43] op_sel_hi:[0,1]
	v_pk_mul_f32 v[40:41], v[202:203], v[40:41] op_sel_hi:[0,1]
	v_pk_mul_f32 v[38:39], v[202:203], v[38:39] op_sel_hi:[0,1]
	v_pk_mul_f32 v[36:37], v[202:203], v[36:37] op_sel_hi:[0,1]
	v_pk_mul_f32 v[34:35], v[202:203], v[34:35] op_sel_hi:[0,1]
	v_pk_mul_f32 v[64:65], v[202:203], v[64:65] op_sel_hi:[0,1]
	v_pk_mul_f32 v[62:63], v[202:203], v[62:63] op_sel_hi:[0,1]
	v_pk_mul_f32 v[60:61], v[202:203], v[60:61] op_sel_hi:[0,1]
	v_pk_mul_f32 v[58:59], v[202:203], v[58:59] op_sel_hi:[0,1]
	v_pk_mul_f32 v[56:57], v[202:203], v[56:57] op_sel_hi:[0,1]
	v_pk_mul_f32 v[54:55], v[202:203], v[54:55] op_sel_hi:[0,1]
	v_pk_mul_f32 v[52:53], v[202:203], v[52:53] op_sel_hi:[0,1]
	v_pk_mul_f32 v[50:51], v[202:203], v[50:51] op_sel_hi:[0,1]
	v_pk_mul_f32 v[80:81], v[202:203], v[80:81] op_sel_hi:[0,1]
	v_pk_mul_f32 v[78:79], v[202:203], v[78:79] op_sel_hi:[0,1]
	v_pk_mul_f32 v[76:77], v[202:203], v[76:77] op_sel_hi:[0,1]
	v_pk_mul_f32 v[74:75], v[202:203], v[74:75] op_sel_hi:[0,1]
	v_pk_mul_f32 v[72:73], v[202:203], v[72:73] op_sel_hi:[0,1]
	v_pk_mul_f32 v[70:71], v[202:203], v[70:71] op_sel_hi:[0,1]
	v_pk_mul_f32 v[68:69], v[202:203], v[68:69] op_sel_hi:[0,1]
	v_pk_mul_f32 v[66:67], v[202:203], v[66:67] op_sel_hi:[0,1]

.LBB0_443:
	v_add3_u32 v198, s20, v180, v182
	ds_read_b128 v[82:85], v198 offset:12800
	ds_read_b128 v[186:189], v198 offset:12832
	s_mul_i32 s12, s19, 0x4800
	v_add_u32_e32 v221, s12, v185
	v_sub_f32_e32 v202, v2, v184
	s_waitcnt lgkmcnt(1)
	v_mfma_f32_32x32x16_bf16 v[82:97], v[82:85], v[98:101], 0
	v_sub_f32_e32 v203, v3, v184
	v_sub_f32_e32 v204, v4, v184
	v_sub_f32_e32 v205, v5, v184
	v_sub_f32_e32 v206, v6, v184
	v_sub_f32_e32 v207, v7, v184
	v_sub_f32_e32 v208, v8, v184
	v_sub_f32_e32 v209, v9, v184
	s_waitcnt lgkmcnt(0)
	v_mfma_f32_32x32x16_bf16 v[82:97], v[186:189], v[102:105], v[82:97]
	ds_read_b128 v[186:189], v198 offset:12864
	ds_read_b128 v[190:193], v198 offset:12896
	v_exp_f32_e32 v217, v202
	v_exp_f32_e32 v218, v203
	v_exp_f32_e32 v219, v204
	v_exp_f32_e32 v220, v205
	v_exp_f32_e32 v206, v206
	v_exp_f32_e32 v207, v207
	s_waitcnt lgkmcnt(1)
	v_mfma_f32_32x32x16_bf16 v[82:97], v[186:189], v[106:109], v[82:97]
	v_exp_f32_e32 v208, v208
	v_exp_f32_e32 v209, v209
	v_sub_f32_e32 v210, v10, v184
	v_sub_f32_e32 v211, v11, v184
	v_sub_f32_e32 v212, v12, v184
	v_sub_f32_e32 v213, v13, v184
	v_sub_f32_e32 v214, v14, v184
	s_waitcnt lgkmcnt(0)
	v_mfma_f32_32x32x16_bf16 v[82:97], v[190:193], v[110:113], v[82:97]
	ds_read_b128 v[186:189], v198 offset:12928
	ds_read_b128 v[190:193], v198 offset:12960
	v_sub_f32_e32 v215, v15, v184
	v_sub_f32_e32 v216, v16, v184
	v_exp_f32_e32 v210, v210
	v_exp_f32_e32 v211, v211
	v_exp_f32_e32 v212, v212
	v_exp_f32_e32 v213, v213
	s_waitcnt lgkmcnt(1)
	v_mfma_f32_32x32x16_bf16 v[82:97], v[186:189], v[114:117], v[82:97]
	ds_read_b128 v[186:189], v198 offset:12992
	v_exp_f32_e32 v214, v214
	v_exp_f32_e32 v215, v215
	v_exp_f32_e32 v216, v216
	v_max_f32_e32 v2, v2, v3
	s_waitcnt lgkmcnt(1)
	v_mfma_f32_32x32x16_bf16 v[82:97], v[190:193], v[118:121], v[82:97]
	ds_read_b128 v[190:193], v198 offset:13024
	v_max3_f32 v2, v2, v4, v5
	v_max3_f32 v2, v2, v6, v7
	v_max3_f32 v2, v2, v8, v9
	v_max3_f32 v6, v2, v10, v11
	v_max3_f32 v6, v6, v12, v13
	v_max3_f32 v6, v6, v14, v15
	s_waitcnt lgkmcnt(1)
	v_mfma_f32_32x32x16_bf16 v[82:97], v[186:189], v[122:125], v[82:97]
	ds_read_b128 v[186:189], v198 offset:13056
	v_max3_f32 v10, v6, v16, v17
	v_add_f32_e32 v12, v218, v217
	ds_bpermute_b32 v11, v178, v10
	s_waitcnt lgkmcnt(2)
	v_mfma_f32_32x32x16_bf16 v[82:97], v[190:193], v[126:129], v[82:97]
	ds_read_b128 v[190:193], v198 offset:13088
	ds_read_b128 v[194:197], v198 offset:13120
	ds_read_b128 v[198:201], v198 offset:13152
	s_waitcnt lgkmcnt(4)
	v_mfma_f32_32x32x16_bf16 v[82:97], v[186:189], v[130:133], v[82:97]
	ds_read_b128 v[186:189], v221 offset:51200
	s_waitcnt lgkmcnt(3)
	v_mfma_f32_32x32x16_bf16 v[82:97], v[190:193], v[134:137], v[82:97]
	ds_read_b128 v[190:193], v221 offset:51232
	s_waitcnt lgkmcnt(3)
	v_mfma_f32_32x32x16_bf16 v[82:97], v[194:197], v[138:141], v[82:97]
	v_cvt_pk_bf16_f32 v194, v217, v218
	v_cvt_pk_bf16_f32 v195, v219, v220
	v_cvt_pk_bf16_f32 v196, v206, v207
	v_cvt_pk_bf16_f32 v197, v208, v209
	s_waitcnt lgkmcnt(1)
	s_nop 0
	v_mfma_f32_32x32x16_bf16 v[18:33], v[186:189], v[194:197], v[18:33]
	v_sub_f32_e32 v186, v17, v184
	v_exp_f32_e32 v222, v186
	v_cvt_pk_bf16_f32 v186, v210, v211
	v_cvt_pk_bf16_f32 v187, v212, v213
	v_cvt_pk_bf16_f32 v188, v214, v215
	v_cvt_pk_bf16_f32 v189, v216, v222
	s_waitcnt lgkmcnt(0)
	s_nop 0
	v_mfma_f32_32x32x16_bf16 v[18:33], v[190:193], v[186:189], v[18:33]
	ds_read_b128 v[190:193], v221 offset:55808
	ds_read_b128 v[202:205], v221 offset:55840
	ds_read_b128 v[2:5], v221 offset:60448
	ds_read_b128 v[6:9], v221 offset:65024
	s_waitcnt lgkmcnt(3)
	v_mfma_f32_32x32x16_bf16 v[34:49], v[190:193], v[194:197], v[34:49]
	ds_read_b128 v[190:193], v221 offset:60416
	s_waitcnt lgkmcnt(0)
	v_mfma_f32_32x32x16_bf16 v[50:65], v[190:193], v[194:197], v[50:65]
	v_mfma_f32_32x32x16_bf16 v[50:65], v[2:5], v[186:189], v[50:65]
	v_add_f32_e32 v2, v219, v12
	v_add_f32_e32 v2, v220, v2
	v_add_f32_e32 v2, v206, v2
	v_add_f32_e32 v2, v207, v2
	v_add_f32_e32 v2, v208, v2
	v_add_f32_e32 v12, v209, v2
	ds_read_b128 v[2:5], v221 offset:65056
	v_mfma_f32_32x32x16_bf16 v[66:81], v[6:9], v[194:197], v[66:81]
	v_add_f32_e32 v6, v210, v12
	v_add_f32_e32 v6, v211, v6
	v_add_f32_e32 v6, v212, v6
	v_add_f32_e32 v6, v213, v6
	v_add_f32_e32 v6, v214, v6
	v_add_f32_e32 v6, v215, v6
	v_add_f32_e32 v6, v216, v6
	s_waitcnt lgkmcnt(0)
	v_mfma_f32_32x32x16_bf16 v[66:81], v[2:5], v[186:189], v[66:81]
	v_add_f32_e32 v2, v222, v6
	v_add_f32_e32 v183, v183, v2
	v_mfma_f32_32x32x16_bf16 v[34:49], v[202:205], v[186:189], v[34:49]
	v_max_f32_e32 v186, v10, v11
	v_sub_f32_e32 v202, v186, v184
	v_cmp_lt_f32_e32 vcc, s2, v202
	v_mfma_f32_32x32x16_bf16 v[2:17], v[198:201], v[142:145], v[82:97]
	s_cbranch_vccz .LBB0_445
	v_max_f32_e32 v202, v202, v202
	v_max_f32_e32 v203, 0, v202
	v_exp_f32_e64 v202, -v203
	v_add_f32_e32 v184, v184, v203
	v_mul_f32_e32 v183, v183, v202
	v_pk_mul_f32 v[32:33], v[32:33], v[202:203] op_sel_hi:[1,0]
	v_pk_mul_f32 v[30:31], v[30:31], v[202:203] op_sel_hi:[1,0]
	v_pk_mul_f32 v[28:29], v[28:29], v[202:203] op_sel_hi:[1,0]
	v_pk_mul_f32 v[26:27], v[26:27], v[202:203] op_sel_hi:[1,0]
	v_pk_mul_f32 v[24:25], v[24:25], v[202:203] op_sel_hi:[1,0]
	v_pk_mul_f32 v[22:23], v[22:23], v[202:203] op_sel_hi:[1,0]
	v_pk_mul_f32 v[20:21], v[20:21], v[202:203] op_sel_hi:[1,0]
	v_pk_mul_f32 v[18:19], v[18:19], v[202:203] op_sel_hi:[1,0]
	v_pk_mul_f32 v[48:49], v[202:203], v[48:49] op_sel_hi:[0,1]
	v_pk_mul_f32 v[46:47], v[202:203], v[46:47] op_sel_hi:[0,1]
	v_pk_mul_f32 v[44:45], v[202:203], v[44:45] op_sel_hi:[0,1]
	v_pk_mul_f32 v[42:43], v[202:203], v[42:43] op_sel_hi:[0,1]
	v_pk_mul_f32 v[40:41], v[202:203], v[40:41] op_sel_hi:[0,1]
	v_pk_mul_f32 v[38:39], v[202:203], v[38:39] op_sel_hi:[0,1]
	v_pk_mul_f32 v[36:37], v[202:203], v[36:37] op_sel_hi:[0,1]
	v_pk_mul_f32 v[34:35], v[202:203], v[34:35] op_sel_hi:[0,1]
	v_pk_mul_f32 v[64:65], v[202:203], v[64:65] op_sel_hi:[0,1]
	v_pk_mul_f32 v[62:63], v[202:203], v[62:63] op_sel_hi:[0,1]
	v_pk_mul_f32 v[60:61], v[202:203], v[60:61] op_sel_hi:[0,1]
	v_pk_mul_f32 v[58:59], v[202:203], v[58:59] op_sel_hi:[0,1]
	v_pk_mul_f32 v[56:57], v[202:203], v[56:57] op_sel_hi:[0,1]
	v_pk_mul_f32 v[54:55], v[202:203], v[54:55] op_sel_hi:[0,1]
	v_pk_mul_f32 v[52:53], v[202:203], v[52:53] op_sel_hi:[0,1]
	v_pk_mul_f32 v[50:51], v[202:203], v[50:51] op_sel_hi:[0,1]
	v_pk_mul_f32 v[80:81], v[202:203], v[80:81] op_sel_hi:[0,1]
	v_pk_mul_f32 v[78:79], v[202:203], v[78:79] op_sel_hi:[0,1]
	v_pk_mul_f32 v[76:77], v[202:203], v[76:77] op_sel_hi:[0,1]
	v_pk_mul_f32 v[74:75], v[202:203], v[74:75] op_sel_hi:[0,1]
	v_pk_mul_f32 v[72:73], v[202:203], v[72:73] op_sel_hi:[0,1]
	v_pk_mul_f32 v[70:71], v[202:203], v[70:71] op_sel_hi:[0,1]
	v_pk_mul_f32 v[68:69], v[202:203], v[68:69] op_sel_hi:[0,1]
	v_pk_mul_f32 v[66:67], v[202:203], v[66:67] op_sel_hi:[0,1]

.LBB0_681:
	v_add3_u32 v1, s21, v209, v213
	ds_read_b128 v[6:9], v1
	ds_read_b128 v[10:13], v1 offset:32
	ds_read_b128 v[96:99], v1 offset:64
	ds_read_b128 v[2:5], v1 offset:96
	s_mulk_i32 s31, 0x4800
	v_add_u32_e32 v132, s31, v223
	ds_read_b128 v[100:103], v132 offset:18496
	ds_read_b128 v[104:107], v132 offset:18528
	ds_read_b128 v[108:111], v132 offset:23104
	ds_read_b128 v[112:115], v132 offset:23136
	ds_read_b128 v[116:119], v132 offset:27712
	ds_read_b128 v[120:123], v132 offset:27744
	ds_read_b128 v[124:127], v132 offset:32320
	ds_read_b128 v[128:131], v132 offset:32352
	s_waitcnt lgkmcnt(11)
	v_mfma_f32_32x32x16_bf16 v[160:175], v[6:9], v[176:179], 0
	v_sub_f32_e32 v7, v16, v217
	v_exp_f32_e32 v7, v7
	v_sub_f32_e32 v9, v17, v217
	v_exp_f32_e32 v9, v9
	v_max_f32_e32 v1, v16, v17
	s_waitcnt lgkmcnt(10)
	v_mfma_f32_32x32x16_bf16 v[160:175], v[10:13], v[180:183], v[160:175]
	v_sub_f32_e32 v10, v18, v217
	v_exp_f32_e32 v11, v10
	v_sub_f32_e32 v10, v19, v217
	v_exp_f32_e32 v12, v10
	v_sub_f32_e32 v10, v20, v217
	v_exp_f32_e32 v13, v10
	v_sub_f32_e32 v10, v21, v217
	v_add_f32_e32 v8, v9, v7
	v_exp_f32_e32 v14, v10
	v_sub_f32_e32 v10, v22, v217
	v_add_f32_e32 v8, v11, v8
	v_exp_f32_e32 v15, v10
	v_sub_f32_e32 v10, v23, v217
	v_max3_f32 v1, v1, v18, v19
	v_add_f32_e32 v8, v12, v8
	v_exp_f32_e32 v16, v10
	v_sub_f32_e32 v10, v24, v217
	v_max3_f32 v1, v1, v20, v21
	v_add_f32_e32 v8, v13, v8
	v_exp_f32_e32 v17, v10
	v_sub_f32_e32 v10, v25, v217
	v_max3_f32 v1, v1, v22, v23
	v_add_f32_e32 v8, v14, v8
	v_exp_f32_e32 v18, v10
	v_sub_f32_e32 v10, v26, v217
	v_max3_f32 v1, v1, v24, v25
	v_add_f32_e32 v8, v15, v8
	v_exp_f32_e32 v19, v10
	v_sub_f32_e32 v10, v27, v217
	v_max3_f32 v1, v1, v26, v27
	v_add_f32_e32 v8, v16, v8
	v_exp_f32_e32 v20, v10
	v_sub_f32_e32 v10, v28, v217
	v_max3_f32 v1, v1, v28, v29
	v_add_f32_e32 v8, v17, v8
	v_exp_f32_e32 v21, v10
	v_sub_f32_e32 v10, v29, v217
	v_max3_f32 v1, v1, v30, v31
	v_add_f32_e32 v8, v18, v8
	v_exp_f32_e32 v22, v10
	v_sub_f32_e32 v10, v30, v217
	ds_bpermute_b32 v6, v247, v1
	v_add_f32_e32 v8, v19, v8
	v_exp_f32_e32 v23, v10
	v_sub_f32_e32 v10, v31, v217
	v_add_f32_e32 v8, v20, v8
	v_exp_f32_e32 v24, v10
	v_add_f32_e32 v8, v21, v8
	v_add_f32_e32 v8, v22, v8
	v_add_f32_e32 v8, v23, v8
	v_add_f32_e32 v8, v24, v8
	s_waitcnt lgkmcnt(0)
	v_max_f32_e32 v210, v1, v6
	v_add_f32_e32 v1, v216, v8
	v_cvt_pk_bf16_f32 v8, v21, v22
	v_cvt_pk_bf16_f32 v10, v7, v9
	v_cvt_pk_bf16_f32 v11, v11, v12
	v_cvt_pk_bf16_f32 v12, v13, v14
	v_cvt_pk_bf16_f32 v13, v15, v16
	v_cvt_pk_bf16_f32 v6, v17, v18
	v_cvt_pk_bf16_f32 v7, v19, v20
	v_mfma_f32_32x32x16_bf16 v[160:175], v[96:99], v[184:187], v[160:175]
	v_cvt_pk_bf16_f32 v9, v23, v24
	v_mfma_f32_32x32x16_bf16 v[32:47], v[100:103], v[10:13], v[32:47]
	v_mfma_f32_32x32x16_bf16 v[48:63], v[108:111], v[10:13], v[48:63]
	v_mfma_f32_32x32x16_bf16 v[48:63], v[112:115], v[6:9], v[48:63]
	v_mfma_f32_32x32x16_bf16 v[64:79], v[116:119], v[10:13], v[64:79]
	v_mfma_f32_32x32x16_bf16 v[64:79], v[120:123], v[6:9], v[64:79]
	v_mfma_f32_32x32x16_bf16 v[80:95], v[124:127], v[10:13], v[80:95]
	v_mfma_f32_32x32x16_bf16 v[32:47], v[104:107], v[6:9], v[32:47]
	v_mfma_f32_32x32x16_bf16 v[80:95], v[128:131], v[6:9], v[80:95]
	v_mfma_f32_32x32x16_bf16 v[16:31], v[2:5], v[188:191], v[160:175]
	v_sub_f32_e32 v2, v210, v217
	v_cmp_lt_f32_e32 vcc, s2, v2
	s_cbranch_vccz .LBB0_698
	v_max_f32_e32 v2, v2, v2
	v_max_f32_e32 v3, 0, v2
	v_exp_f32_e64 v2, -v3
	v_add_f32_e32 v6, v217, v3
	v_mul_f32_e32 v1, v2, v1
	s_nop 3
	v_pk_mul_f32 v[46:47], v[46:47], v[2:3] op_sel_hi:[1,0]
	v_pk_mul_f32 v[44:45], v[44:45], v[2:3] op_sel_hi:[1,0]
	v_pk_mul_f32 v[42:43], v[42:43], v[2:3] op_sel_hi:[1,0]
	v_pk_mul_f32 v[40:41], v[40:41], v[2:3] op_sel_hi:[1,0]
	v_pk_mul_f32 v[38:39], v[38:39], v[2:3] op_sel_hi:[1,0]
	v_pk_mul_f32 v[36:37], v[36:37], v[2:3] op_sel_hi:[1,0]
	v_pk_mul_f32 v[34:35], v[34:35], v[2:3] op_sel_hi:[1,0]
	v_pk_mul_f32 v[32:33], v[32:33], v[2:3] op_sel_hi:[1,0]
	v_pk_mul_f32 v[62:63], v[62:63], v[2:3] op_sel_hi:[1,0]
	v_pk_mul_f32 v[60:61], v[60:61], v[2:3] op_sel_hi:[1,0]
	v_pk_mul_f32 v[58:59], v[58:59], v[2:3] op_sel_hi:[1,0]
	v_pk_mul_f32 v[56:57], v[56:57], v[2:3] op_sel_hi:[1,0]
	v_pk_mul_f32 v[54:55], v[54:55], v[2:3] op_sel_hi:[1,0]
	v_pk_mul_f32 v[52:53], v[52:53], v[2:3] op_sel_hi:[1,0]
	v_pk_mul_f32 v[50:51], v[50:51], v[2:3] op_sel_hi:[1,0]
	v_pk_mul_f32 v[48:49], v[48:49], v[2:3] op_sel_hi:[1,0]
	v_pk_mul_f32 v[78:79], v[2:3], v[78:79] op_sel_hi:[0,1]
	v_pk_mul_f32 v[76:77], v[2:3], v[76:77] op_sel_hi:[0,1]
	v_pk_mul_f32 v[74:75], v[2:3], v[74:75] op_sel_hi:[0,1]
	v_pk_mul_f32 v[72:73], v[2:3], v[72:73] op_sel_hi:[0,1]
	v_pk_mul_f32 v[70:71], v[2:3], v[70:71] op_sel_hi:[0,1]
	v_pk_mul_f32 v[68:69], v[2:3], v[68:69] op_sel_hi:[0,1]
	v_pk_mul_f32 v[66:67], v[2:3], v[66:67] op_sel_hi:[0,1]
	v_pk_mul_f32 v[64:65], v[2:3], v[64:65] op_sel_hi:[0,1]
	v_pk_mul_f32 v[94:95], v[2:3], v[94:95] op_sel_hi:[0,1]
	v_pk_mul_f32 v[92:93], v[2:3], v[92:93] op_sel_hi:[0,1]
	v_pk_mul_f32 v[90:91], v[2:3], v[90:91] op_sel_hi:[0,1]
	v_pk_mul_f32 v[88:89], v[2:3], v[88:89] op_sel_hi:[0,1]
	v_pk_mul_f32 v[86:87], v[2:3], v[86:87] op_sel_hi:[0,1]
	v_pk_mul_f32 v[84:85], v[2:3], v[84:85] op_sel_hi:[0,1]
	v_pk_mul_f32 v[82:83], v[2:3], v[82:83] op_sel_hi:[0,1]
	v_pk_mul_f32 v[80:81], v[2:3], v[80:81] op_sel_hi:[0,1]
	s_cbranch_execz .LBB0_685
	s_branch .LBB0_686

.LBB0_694:
	v_add3_u32 v119, s21, v209, v213
	ds_read_b128 v[2:5], v119 offset:4608
	ds_read_b128 v[10:13], v119 offset:4640
	s_mul_i32 s21, s19, 0x4800
	v_add_u32_e32 v132, s21, v223
	ds_read_b128 v[124:127], v132 offset:18432
	ds_read_b128 v[128:131], v132 offset:18464
	ds_read_b128 v[134:137], v132 offset:23040
	ds_read_b128 v[138:141], v132 offset:23072
	ds_read_b128 v[142:145], v132 offset:27648
	ds_read_b128 v[146:149], v132 offset:27680
	ds_read_b128 v[150:153], v132 offset:32256
	ds_read_b128 v[154:157], v132 offset:32288
	v_sub_f32_e32 v113, v22, v6
	v_sub_f32_e32 v14, v19, v6
	v_sub_f32_e32 v114, v23, v6
	v_sub_f32_e32 v15, v20, v6
	v_sub_f32_e32 v115, v24, v6
	s_waitcnt lgkmcnt(9)
	v_mfma_f32_32x32x16_bf16 v[96:111], v[2:5], v[176:179], 0
	ds_read_b128 v[2:5], v119 offset:4672
	v_sub_f32_e32 v7, v16, v6
	v_sub_f32_e32 v8, v17, v6
	v_sub_f32_e32 v9, v18, v6
	v_sub_f32_e32 v112, v21, v6
	v_exp_f32_e32 v7, v7
	s_waitcnt lgkmcnt(9)
	v_mfma_f32_32x32x16_bf16 v[96:111], v[10:13], v[180:183], v[96:111]
	v_exp_f32_e32 v13, v113
	v_exp_f32_e32 v10, v14
	v_exp_f32_e32 v14, v114
	v_exp_f32_e32 v11, v15
	v_exp_f32_e32 v15, v115
	v_exp_f32_e32 v8, v8
	v_exp_f32_e32 v9, v9
	s_waitcnt lgkmcnt(0)
	v_mfma_f32_32x32x16_bf16 v[96:111], v[2:5], v[184:187], v[96:111]
	v_sub_f32_e32 v2, v26, v6
	v_exp_f32_e32 v113, v2
	v_sub_f32_e32 v2, v27, v6
	v_exp_f32_e32 v114, v2
	v_sub_f32_e32 v2, v28, v6
	v_exp_f32_e32 v115, v2
	v_exp_f32_e32 v12, v112
	v_cvt_pk_bf16_f32 v120, v7, v8
	v_cvt_pk_bf16_f32 v121, v9, v10
	v_cvt_pk_bf16_f32 v123, v13, v14
	v_cvt_pk_bf16_f32 v122, v11, v12
	v_sub_f32_e32 v116, v25, v6
	v_exp_f32_e32 v112, v116
	v_mfma_f32_32x32x16_bf16 v[32:47], v[124:127], v[120:123], v[32:47]
	ds_read_b128 v[124:127], v119 offset:4704
	v_sub_f32_e32 v116, v29, v6
	v_sub_f32_e32 v117, v30, v6
	v_sub_f32_e32 v2, v31, v6
	v_exp_f32_e32 v116, v116
	v_exp_f32_e32 v117, v117
	v_exp_f32_e32 v118, v2
	v_cvt_pk_bf16_f32 v2, v15, v112
	v_cvt_pk_bf16_f32 v3, v113, v114
	v_cvt_pk_bf16_f32 v4, v115, v116
	v_cvt_pk_bf16_f32 v5, v117, v118
	v_max_f32_e32 v16, v16, v17
	v_max3_f32 v16, v16, v18, v19
	v_mfma_f32_32x32x16_bf16 v[32:47], v[128:131], v[2:5], v[32:47]
	v_max3_f32 v16, v16, v20, v21
	v_max3_f32 v16, v16, v22, v23
	v_max3_f32 v20, v16, v24, v25
	v_mfma_f32_32x32x16_bf16 v[48:63], v[134:137], v[120:123], v[48:63]
	v_max3_f32 v20, v20, v26, v27
	v_max3_f32 v20, v20, v28, v29
	v_max3_f32 v20, v20, v30, v31
	ds_bpermute_b32 v21, v247, v20
	s_andn2_b64 vcc, exec, s[92:93]
	v_mfma_f32_32x32x16_bf16 v[48:63], v[138:141], v[2:5], v[48:63]
	v_mfma_f32_32x32x16_bf16 v[64:79], v[142:145], v[120:123], v[64:79]
	v_mfma_f32_32x32x16_bf16 v[80:95], v[150:153], v[120:123], v[80:95]
	v_mfma_f32_32x32x16_bf16 v[64:79], v[146:149], v[2:5], v[64:79]
	v_mfma_f32_32x32x16_bf16 v[80:95], v[154:157], v[2:5], v[80:95]
	s_waitcnt lgkmcnt(0)
	v_max_f32_e32 v2, v20, v21
	v_sub_f32_e32 v2, v2, v6
	v_mfma_f32_32x32x16_bf16 v[16:31], v[124:127], v[188:191], v[96:111]
	s_cbranch_vccnz .LBB0_697
	v_cmp_lt_f32_e32 vcc, s2, v2
	s_cbranch_vccz .LBB0_699
	v_max_f32_e32 v2, v2, v2
	v_max_f32_e32 v2, 0, v2

.LBB0_700:
	v_add_f32_e32 v3, v8, v7
	v_add_f32_e32 v3, v9, v3
	v_add_f32_e32 v3, v10, v3
	v_add_f32_e32 v3, v11, v3
	v_add_f32_e32 v3, v12, v3
	v_add_f32_e32 v3, v13, v3
	v_add_f32_e32 v3, v14, v3
	v_add_f32_e32 v3, v15, v3
	v_add_f32_e32 v3, v112, v3
	v_add_f32_e32 v3, v113, v3
	v_add_f32_e32 v3, v114, v3
	v_add_f32_e32 v3, v115, v3
	v_add_f32_e32 v3, v116, v3
	v_add_f32_e32 v3, v117, v3
	v_add_f32_e32 v3, v118, v3
	v_add_f32_e32 v1, v1, v3
	s_and_b64 vcc, exec, s[48:49]
	s_cbranch_vccz .LBB0_702
	v_exp_f32_e64 v4, -v2
	v_add_f32_e32 v6, v6, v2
	v_mul_f32_e32 v1, v1, v4
	v_pk_mul_f32 v[46:47], v[46:47], v[4:5] op_sel_hi:[1,0]
	v_pk_mul_f32 v[44:45], v[44:45], v[4:5] op_sel_hi:[1,0]
	v_pk_mul_f32 v[42:43], v[42:43], v[4:5] op_sel_hi:[1,0]
	v_pk_mul_f32 v[40:41], v[40:41], v[4:5] op_sel_hi:[1,0]
	v_pk_mul_f32 v[38:39], v[38:39], v[4:5] op_sel_hi:[1,0]
	v_pk_mul_f32 v[36:37], v[36:37], v[4:5] op_sel_hi:[1,0]
	v_pk_mul_f32 v[34:35], v[34:35], v[4:5] op_sel_hi:[1,0]
	v_pk_mul_f32 v[32:33], v[32:33], v[4:5] op_sel_hi:[1,0]
	v_pk_mul_f32 v[62:63], v[62:63], v[4:5] op_sel_hi:[1,0]
	v_pk_mul_f32 v[60:61], v[60:61], v[4:5] op_sel_hi:[1,0]
	v_pk_mul_f32 v[58:59], v[58:59], v[4:5] op_sel_hi:[1,0]
	v_pk_mul_f32 v[56:57], v[56:57], v[4:5] op_sel_hi:[1,0]
	v_pk_mul_f32 v[54:55], v[54:55], v[4:5] op_sel_hi:[1,0]
	v_pk_mul_f32 v[52:53], v[52:53], v[4:5] op_sel_hi:[1,0]
	v_pk_mul_f32 v[50:51], v[50:51], v[4:5] op_sel_hi:[1,0]
	v_pk_mul_f32 v[48:49], v[48:49], v[4:5] op_sel_hi:[1,0]
	v_pk_mul_f32 v[78:79], v[78:79], v[4:5] op_sel_hi:[1,0]
	v_pk_mul_f32 v[76:77], v[76:77], v[4:5] op_sel_hi:[1,0]
	v_pk_mul_f32 v[74:75], v[74:75], v[4:5] op_sel_hi:[1,0]
	v_pk_mul_f32 v[72:73], v[72:73], v[4:5] op_sel_hi:[1,0]
	v_pk_mul_f32 v[70:71], v[70:71], v[4:5] op_sel_hi:[1,0]
	v_pk_mul_f32 v[68:69], v[68:69], v[4:5] op_sel_hi:[1,0]
	v_pk_mul_f32 v[66:67], v[66:67], v[4:5] op_sel_hi:[1,0]
	v_pk_mul_f32 v[64:65], v[64:65], v[4:5] op_sel_hi:[1,0]
	v_pk_mul_f32 v[94:95], v[94:95], v[4:5] op_sel_hi:[1,0]
	v_pk_mul_f32 v[92:93], v[92:93], v[4:5] op_sel_hi:[1,0]
	v_pk_mul_f32 v[90:91], v[90:91], v[4:5] op_sel_hi:[1,0]
	v_pk_mul_f32 v[88:89], v[88:89], v[4:5] op_sel_hi:[1,0]
	v_pk_mul_f32 v[86:87], v[86:87], v[4:5] op_sel_hi:[1,0]
	v_pk_mul_f32 v[84:85], v[84:85], v[4:5] op_sel_hi:[1,0]
	v_pk_mul_f32 v[82:83], v[82:83], v[4:5] op_sel_hi:[1,0]
	v_pk_mul_f32 v[80:81], v[80:81], v[4:5] op_sel_hi:[1,0]
